# mix dynamic queue: fetch atomic issued before the unit-end workgroup barrier
# speedup vs baseline: 1.0038x; 1.0028x over previous
.LBB0_1056:
	v_mov_b32_e32 v144, v139
	s_cmpk_gt_i32 s16, 0xff
	s_cbranch_scc0 .LBB0_1065
	v_cmp_eq_u32_e32 vcc, 0, v144
	s_and_saveexec_b64 s[0:1], vcc
	s_cbranch_execz .Lfetch_a
	s_mov_b64 s[12:13], exec
	v_mbcnt_lo_u32_b32 v0, s12, 0
	v_mbcnt_hi_u32_b32 v0, s13, v0
	v_cmp_eq_u32_e32 vcc, 0, v0
	s_and_saveexec_b64 s[4:5], vcc
	s_cbranch_execz .Lfetch_b
	s_bcnt1_i32_b64 s12, s[12:13]
	v_mov_b32_e32 v1, s12
	global_atomic_add v1, v4, v1, s[6:7] sc0

.Lfetch_a:
	s_or_b64 exec, exec, s[0:1]
	s_barrier
	s_and_saveexec_b64 s[0:1], s[94:95]
	s_cbranch_execz .LBB0_1061
	s_waitcnt vmcnt(0)
	v_readfirstlane_b32 s4, v1
	s_nop 1
	v_add_u32_e32 v0, s4, v0
	v_add_u32_e32 v0, 0x100, v0
	ds_write_b32 v4, v0 offset:16
